# v17 + ssm Y epilogue: 32 serialized u-loads hoisted above the stores
# baseline (speedup 1.0000x reference)
.LBB0_104:
	s_lshl_b32 s4, s4, 4
	s_ashr_i32 s5, s4, 31
	v_mov_b32_e32 v14, v152
	v_mov_b32_e32 v135, v153
	s_lshl_b64 s[6:7], s[4:5], 2
	s_add_u32 s6, s40, s6
	v_lshlrev_b32_e32 v144, 2, v14
	s_addc_u32 s7, s41, s7
	v_ashrrev_i32_e32 v145, 31, v144
	v_add3_u32 v148, s15, v156, v135
	v_lshl_add_u64 v[14:15], v[144:145], 2, s[6:7]
	v_lshlrev_b64 v[144:145], 1, v[144:145]
	v_ashrrev_i32_e32 v149, 31, v148
	v_lshl_add_u64 v[146:147], s[2:3], 0, v[144:145]
	v_lshlrev_b64 v[150:151], 9, v[148:149]
	v_lshl_add_u64 v[150:151], v[146:147], 0, v[150:151]
	global_load_dwordx4 v[14:17], v[14:15], off
	s_mov_b32 s98, 0x2000
	s_mov_b32 s99, 0
	v_lshl_add_u64 v[190:191], v[150:151], 0, v[0:1]
	v_mov_b32_e32 v218, v138
	v_mov_b32_e32 v219, v1
	v_lshl_add_u64 v[218:219], v[150:151], 0, v[218:219]
	global_load_dwordx2 v[166:167], v[190:191], off
	global_load_dwordx2 v[168:169], v[218:219], off
	s_nop 0
	v_lshl_add_u64 v[190:191], v[190:191], 0, s[98:99]
	v_lshl_add_u64 v[218:219], v[218:219], 0, s[98:99]
	global_load_dwordx2 v[174:175], v[190:191], off
	global_load_dwordx2 v[192:193], v[218:219], off
	s_nop 0
	v_lshl_add_u64 v[190:191], v[190:191], 0, s[98:99]
	v_lshl_add_u64 v[218:219], v[218:219], 0, s[98:99]
	global_load_dwordx2 v[198:199], v[190:191], off
	global_load_dwordx2 v[200:201], v[218:219], off
	s_nop 0
	v_lshl_add_u64 v[190:191], v[190:191], 0, s[98:99]
	v_lshl_add_u64 v[218:219], v[218:219], 0, s[98:99]
	global_load_dwordx2 v[206:207], v[190:191], off
	global_load_dwordx2 v[208:209], v[218:219], off
	s_nop 0
	v_lshl_add_u64 v[190:191], v[190:191], 0, s[98:99]
	v_lshl_add_u64 v[218:219], v[218:219], 0, s[98:99]
	global_load_dwordx2 v[214:215], v[190:191], off
	global_load_dwordx2 v[216:217], v[218:219], off
	s_nop 0
	v_lshl_add_u64 v[190:191], v[190:191], 0, s[98:99]
	v_lshl_add_u64 v[218:219], v[218:219], 0, s[98:99]
	global_load_dwordx2 v[226:227], v[190:191], off
	global_load_dwordx2 v[228:229], v[218:219], off
	s_nop 0
	v_lshl_add_u64 v[190:191], v[190:191], 0, s[98:99]
	v_lshl_add_u64 v[218:219], v[218:219], 0, s[98:99]
	global_load_dwordx2 v[234:235], v[190:191], off
	global_load_dwordx2 v[236:237], v[218:219], off
	s_nop 0
	v_lshl_add_u64 v[190:191], v[190:191], 0, s[98:99]
	v_lshl_add_u64 v[218:219], v[218:219], 0, s[98:99]
	global_load_dwordx2 v[242:243], v[190:191], off
	global_load_dwordx2 v[244:245], v[218:219], off
	s_nop 0
	v_mov_b32_e32 v190, v140
	v_mov_b32_e32 v191, v1
	v_lshl_add_u64 v[190:191], v[150:151], 0, v[190:191]
	v_mov_b32_e32 v218, v142
	v_mov_b32_e32 v219, v1
	v_lshl_add_u64 v[218:219], v[150:151], 0, v[218:219]
	global_load_dwordx2 v[170:171], v[190:191], off
	global_load_dwordx2 v[172:173], v[218:219], off
	s_nop 0
	v_lshl_add_u64 v[190:191], v[190:191], 0, s[98:99]
	v_lshl_add_u64 v[218:219], v[218:219], 0, s[98:99]
	global_load_dwordx2 v[194:195], v[190:191], off
	global_load_dwordx2 v[196:197], v[218:219], off
	s_nop 0
	v_lshl_add_u64 v[190:191], v[190:191], 0, s[98:99]
	v_lshl_add_u64 v[218:219], v[218:219], 0, s[98:99]
	global_load_dwordx2 v[202:203], v[190:191], off
	global_load_dwordx2 v[204:205], v[218:219], off
	s_nop 0
	v_lshl_add_u64 v[190:191], v[190:191], 0, s[98:99]
	v_lshl_add_u64 v[218:219], v[218:219], 0, s[98:99]
	global_load_dwordx2 v[210:211], v[190:191], off
	global_load_dwordx2 v[212:213], v[218:219], off
	s_nop 0
	v_lshl_add_u64 v[190:191], v[190:191], 0, s[98:99]
	v_lshl_add_u64 v[218:219], v[218:219], 0, s[98:99]
	global_load_dwordx2 v[222:223], v[190:191], off
	global_load_dwordx2 v[224:225], v[218:219], off
	s_nop 0
	v_lshl_add_u64 v[190:191], v[190:191], 0, s[98:99]
	v_lshl_add_u64 v[218:219], v[218:219], 0, s[98:99]
	global_load_dwordx2 v[230:231], v[190:191], off
	global_load_dwordx2 v[232:233], v[218:219], off
	s_nop 0
	v_lshl_add_u64 v[190:191], v[190:191], 0, s[98:99]
	v_lshl_add_u64 v[218:219], v[218:219], 0, s[98:99]
	global_load_dwordx2 v[238:239], v[190:191], off
	global_load_dwordx2 v[240:241], v[218:219], off
	s_nop 0
	v_lshl_add_u64 v[190:191], v[190:191], 0, s[98:99]
	v_lshl_add_u64 v[218:219], v[218:219], 0, s[98:99]
	global_load_dwordx2 v[246:247], v[190:191], off
	global_load_dwordx2 v[248:249], v[218:219], off
	s_lshl_b64 s[2:3], s[4:5], 1
	v_lshlrev_b32_e32 v135, 4, v148
	s_add_u32 s2, s51, s2
	s_addc_u32 s3, s57, s3
	v_lshl_add_u64 v[144:145], s[2:3], 0, v[144:145]
	v_mov_b32_e32 v141, v1
	v_mov_b32_e32 v143, v1
	s_waitcnt vmcnt(0)
	s_nop 1
	v_mov_b32_e32 v162, v166
	v_mov_b32_e32 v163, v167
	v_lshlrev_b32_e32 v164, 16, v162
	v_and_b32_e32 v165, 0xffff0000, v162
	v_pk_fma_f32 v[130:131], v[14:15], v[164:165], v[130:131]
	v_lshlrev_b32_e32 v162, 16, v163
	v_pk_mul_f32 v[164:165], v[130:131], v[130:131]
	v_and_b32_e32 v163, 0xffff0000, v163
	v_fmamk_f32 v139, v164, 0xbdd2d3e8, v178
	v_mul_f32_e32 v139, v130, v139
	v_exp_f32_e32 v139, v139
	v_pk_fma_f32 v[132:133], v[16:17], v[162:163], v[132:133]
	v_add_f32_e32 v139, 1.0, v139
	v_rcp_f32_e32 v164, v139
	v_fmamk_f32 v139, v165, 0xbdd2d3e8, v178
	v_mul_f32_e32 v139, v131, v139
	v_exp_f32_e32 v139, v139
	v_pk_mul_f32 v[162:163], v[132:133], v[132:133]
	v_add_f32_e32 v139, 1.0, v139
	v_rcp_f32_e32 v165, v139
	v_mov_b32_e32 v139, v1
	v_pk_mul_f32 v[130:131], v[130:131], v[164:165]
	s_nop 0
	v_cvt_pk_bf16_f32 v130, v130, v131
	v_fmamk_f32 v131, v162, 0xbdd2d3e8, v178
	v_mul_f32_e32 v131, v132, v131
	v_exp_f32_e32 v131, v131
	s_nop 0
	v_add_f32_e32 v131, 1.0, v131
	v_rcp_f32_e32 v162, v131
	v_fmamk_f32 v131, v163, 0xbdd2d3e8, v178
	v_mul_f32_e32 v131, v133, v131
	v_exp_f32_e32 v131, v131
	s_nop 0
	v_add_f32_e32 v131, 1.0, v131
	v_rcp_f32_e32 v163, v131
	s_nop 0
	v_pk_mul_f32 v[132:133], v[132:133], v[162:163]
	s_nop 0
	v_cvt_pk_bf16_f32 v131, v132, v133
	v_or_b32_e32 v132, v135, v157
	v_ashrrev_i32_e32 v133, 31, v132
	v_lshlrev_b64 v[132:133], 11, v[132:133]
	v_lshl_add_u64 v[132:133], v[144:145], 0, v[132:133]
	global_store_dwordx2 v[132:133], v[130:131], off
	s_nop 1
	v_mov_b32_e32 v130, v168
	v_mov_b32_e32 v131, v169
	v_lshlrev_b32_e32 v132, 16, v130
	v_and_b32_e32 v133, 0xffff0000, v130
	v_pk_fma_f32 v[126:127], v[14:15], v[132:133], v[126:127]
	s_nop 0
	v_pk_mul_f32 v[132:133], v[126:127], v[126:127]
	s_nop 0
	v_fmamk_f32 v130, v132, 0xbdd2d3e8, v178
	v_mul_f32_e32 v130, v126, v130
	v_exp_f32_e32 v130, v130
	s_nop 0
	v_add_f32_e32 v130, 1.0, v130
	v_rcp_f32_e32 v132, v130
	v_fmamk_f32 v130, v133, 0xbdd2d3e8, v178
	v_mul_f32_e32 v130, v127, v130
	v_exp_f32_e32 v130, v130
	s_nop 0
	v_add_f32_e32 v130, 1.0, v130
	v_rcp_f32_e32 v133, v130
	v_lshlrev_b32_e32 v130, 16, v131
	v_and_b32_e32 v131, 0xffff0000, v131
	v_pk_fma_f32 v[128:129], v[16:17], v[130:131], v[128:129]
	v_pk_mul_f32 v[126:127], v[126:127], v[132:133]
	v_pk_mul_f32 v[130:131], v[128:129], v[128:129]
	v_cvt_pk_bf16_f32 v126, v126, v127
	v_fmamk_f32 v127, v130, 0xbdd2d3e8, v178
	v_mul_f32_e32 v127, v128, v127
	v_exp_f32_e32 v127, v127
	s_nop 0
	v_add_f32_e32 v127, 1.0, v127
	v_rcp_f32_e32 v130, v127
	v_fmamk_f32 v127, v131, 0xbdd2d3e8, v178
	v_mul_f32_e32 v127, v129, v127
	v_exp_f32_e32 v127, v127
	s_nop 0
	v_add_f32_e32 v127, 1.0, v127
	v_rcp_f32_e32 v131, v127
	s_nop 0
	v_pk_mul_f32 v[128:129], v[128:129], v[130:131]
	s_nop 0
	v_cvt_pk_bf16_f32 v127, v128, v129
	v_or_b32_e32 v128, v135, v158
	v_ashrrev_i32_e32 v129, 31, v128
	v_lshlrev_b64 v[128:129], 11, v[128:129]
	v_lshl_add_u64 v[128:129], v[144:145], 0, v[128:129]
	global_store_dwordx2 v[128:129], v[126:127], off
	s_nop 1
	v_mov_b32_e32 v126, v170
	v_mov_b32_e32 v127, v171
	v_lshlrev_b32_e32 v128, 16, v126
	v_and_b32_e32 v129, 0xffff0000, v126
	v_pk_fma_f32 v[122:123], v[14:15], v[128:129], v[122:123]
	s_nop 0
	v_pk_mul_f32 v[128:129], v[122:123], v[122:123]
	s_nop 0
	v_fmamk_f32 v126, v128, 0xbdd2d3e8, v178
	v_mul_f32_e32 v126, v122, v126
	v_exp_f32_e32 v126, v126
	s_nop 0
	v_add_f32_e32 v126, 1.0, v126
	v_rcp_f32_e32 v128, v126
	v_fmamk_f32 v126, v129, 0xbdd2d3e8, v178
	v_mul_f32_e32 v126, v123, v126
	v_exp_f32_e32 v126, v126
	s_nop 0
	v_add_f32_e32 v126, 1.0, v126
	v_rcp_f32_e32 v129, v126
	v_lshlrev_b32_e32 v126, 16, v127
	v_and_b32_e32 v127, 0xffff0000, v127
	v_pk_fma_f32 v[124:125], v[16:17], v[126:127], v[124:125]
	v_pk_mul_f32 v[122:123], v[122:123], v[128:129]
	v_pk_mul_f32 v[126:127], v[124:125], v[124:125]
	v_cvt_pk_bf16_f32 v122, v122, v123
	v_fmamk_f32 v123, v126, 0xbdd2d3e8, v178
	v_mul_f32_e32 v123, v124, v123
	v_exp_f32_e32 v123, v123
	s_nop 0
	v_add_f32_e32 v123, 1.0, v123
	v_rcp_f32_e32 v126, v123
	v_fmamk_f32 v123, v127, 0xbdd2d3e8, v178
	v_mul_f32_e32 v123, v125, v123
	v_exp_f32_e32 v123, v123
	s_nop 0
	v_add_f32_e32 v123, 1.0, v123
	v_rcp_f32_e32 v127, v123
	s_nop 0
	v_pk_mul_f32 v[124:125], v[124:125], v[126:127]
	s_nop 0
	v_cvt_pk_bf16_f32 v123, v124, v125
	v_or_b32_e32 v124, v135, v159
	v_ashrrev_i32_e32 v125, 31, v124
	v_lshlrev_b64 v[124:125], 11, v[124:125]
	v_lshl_add_u64 v[124:125], v[144:145], 0, v[124:125]
	global_store_dwordx2 v[124:125], v[122:123], off
	s_nop 1
	v_mov_b32_e32 v122, v172
	v_mov_b32_e32 v123, v173
	v_lshlrev_b32_e32 v124, 16, v122
	v_and_b32_e32 v125, 0xffff0000, v122
	v_pk_fma_f32 v[118:119], v[14:15], v[124:125], v[118:119]
	s_nop 0
	v_pk_mul_f32 v[124:125], v[118:119], v[118:119]
	s_nop 0
	v_fmamk_f32 v122, v124, 0xbdd2d3e8, v178
	v_mul_f32_e32 v122, v118, v122
	v_exp_f32_e32 v122, v122
	s_nop 0
	v_add_f32_e32 v122, 1.0, v122
	v_rcp_f32_e32 v124, v122
	v_fmamk_f32 v122, v125, 0xbdd2d3e8, v178
	v_mul_f32_e32 v122, v119, v122
	v_exp_f32_e32 v122, v122
	s_nop 0
	v_add_f32_e32 v122, 1.0, v122
	v_rcp_f32_e32 v125, v122
	v_lshlrev_b32_e32 v122, 16, v123
	v_and_b32_e32 v123, 0xffff0000, v123
	v_pk_fma_f32 v[120:121], v[16:17], v[122:123], v[120:121]
	v_pk_mul_f32 v[118:119], v[118:119], v[124:125]
	v_pk_mul_f32 v[122:123], v[120:121], v[120:121]
	v_cvt_pk_bf16_f32 v118, v118, v119
	v_fmamk_f32 v119, v122, 0xbdd2d3e8, v178
	v_mul_f32_e32 v119, v120, v119
	v_exp_f32_e32 v119, v119
	s_nop 0
	v_add_f32_e32 v119, 1.0, v119
	v_rcp_f32_e32 v122, v119
	v_fmamk_f32 v119, v123, 0xbdd2d3e8, v178
	v_mul_f32_e32 v119, v121, v119
	v_exp_f32_e32 v119, v119
	s_nop 0
	v_add_f32_e32 v119, 1.0, v119
	v_rcp_f32_e32 v123, v119
	s_nop 0
	v_pk_mul_f32 v[120:121], v[120:121], v[122:123]
	s_nop 0
	v_cvt_pk_bf16_f32 v119, v120, v121
	v_or_b32_e32 v120, v135, v160
	v_ashrrev_i32_e32 v121, 31, v120
	v_lshlrev_b64 v[120:121], 11, v[120:121]
	v_lshl_add_u64 v[120:121], v[144:145], 0, v[120:121]
	global_store_dwordx2 v[120:121], v[118:119], off
	v_add_u32_e32 v120, 16, v148
	v_ashrrev_i32_e32 v121, 31, v120
	v_lshlrev_b64 v[118:119], 9, v[120:121]
	v_lshl_add_u64 v[118:119], v[146:147], 0, v[118:119]
	v_lshlrev_b32_e32 v120, 4, v120
	s_nop 1
	v_mov_b32_e32 v122, v174
	v_mov_b32_e32 v123, v175
	v_lshlrev_b32_e32 v124, 16, v122
	v_and_b32_e32 v125, 0xffff0000, v122
	v_pk_fma_f32 v[114:115], v[14:15], v[124:125], v[114:115]
	v_lshlrev_b32_e32 v122, 16, v123
	v_pk_mul_f32 v[124:125], v[114:115], v[114:115]
	v_and_b32_e32 v123, 0xffff0000, v123
	v_fmamk_f32 v121, v124, 0xbdd2d3e8, v178
	v_mul_f32_e32 v121, v114, v121
	v_exp_f32_e32 v121, v121
	v_pk_fma_f32 v[116:117], v[16:17], v[122:123], v[116:117]
	v_add_f32_e32 v121, 1.0, v121
	v_rcp_f32_e32 v124, v121
	v_fmamk_f32 v121, v125, 0xbdd2d3e8, v178
	v_mul_f32_e32 v121, v115, v121
	v_exp_f32_e32 v121, v121
	v_pk_mul_f32 v[122:123], v[116:117], v[116:117]
	v_add_f32_e32 v121, 1.0, v121
	v_rcp_f32_e32 v125, v121
	s_nop 0
	v_pk_mul_f32 v[114:115], v[114:115], v[124:125]
	s_nop 0
	v_cvt_pk_bf16_f32 v114, v114, v115
	v_fmamk_f32 v115, v122, 0xbdd2d3e8, v178
	v_mul_f32_e32 v115, v116, v115
	v_exp_f32_e32 v115, v115
	s_nop 0
	v_add_f32_e32 v115, 1.0, v115
	v_rcp_f32_e32 v122, v115
	v_fmamk_f32 v115, v123, 0xbdd2d3e8, v178
	v_mul_f32_e32 v115, v117, v115
	v_exp_f32_e32 v115, v115
	s_nop 0
	v_add_f32_e32 v115, 1.0, v115
	v_rcp_f32_e32 v123, v115
	s_nop 0
	v_pk_mul_f32 v[116:117], v[116:117], v[122:123]
	s_nop 0
	v_cvt_pk_bf16_f32 v115, v116, v117
	v_or_b32_e32 v116, v120, v157
	v_ashrrev_i32_e32 v117, 31, v116
	v_lshlrev_b64 v[116:117], 11, v[116:117]
	v_lshl_add_u64 v[116:117], v[144:145], 0, v[116:117]
	global_store_dwordx2 v[116:117], v[114:115], off
	s_nop 1
	v_mov_b32_e32 v114, v192
	v_mov_b32_e32 v115, v193
	v_lshlrev_b32_e32 v116, 16, v114
	v_and_b32_e32 v117, 0xffff0000, v114
	v_pk_fma_f32 v[110:111], v[14:15], v[116:117], v[110:111]
	s_nop 0
	v_pk_mul_f32 v[116:117], v[110:111], v[110:111]
	s_nop 0
	v_fmamk_f32 v114, v116, 0xbdd2d3e8, v178
	v_mul_f32_e32 v114, v110, v114
	v_exp_f32_e32 v114, v114
	s_nop 0
	v_add_f32_e32 v114, 1.0, v114
	v_rcp_f32_e32 v116, v114
	v_fmamk_f32 v114, v117, 0xbdd2d3e8, v178
	v_mul_f32_e32 v114, v111, v114
	v_exp_f32_e32 v114, v114
	s_nop 0
	v_add_f32_e32 v114, 1.0, v114
	v_rcp_f32_e32 v117, v114
	v_lshlrev_b32_e32 v114, 16, v115
	v_and_b32_e32 v115, 0xffff0000, v115
	v_pk_fma_f32 v[112:113], v[16:17], v[114:115], v[112:113]
	v_pk_mul_f32 v[110:111], v[110:111], v[116:117]
	v_pk_mul_f32 v[114:115], v[112:113], v[112:113]
	v_cvt_pk_bf16_f32 v110, v110, v111
	v_fmamk_f32 v111, v114, 0xbdd2d3e8, v178
	v_mul_f32_e32 v111, v112, v111
	v_exp_f32_e32 v111, v111
	s_nop 0
	v_add_f32_e32 v111, 1.0, v111
	v_rcp_f32_e32 v114, v111
	v_fmamk_f32 v111, v115, 0xbdd2d3e8, v178
	v_mul_f32_e32 v111, v113, v111
	v_exp_f32_e32 v111, v111
	s_nop 0
	v_add_f32_e32 v111, 1.0, v111
	v_rcp_f32_e32 v115, v111
	s_nop 0
	v_pk_mul_f32 v[112:113], v[112:113], v[114:115]
	s_nop 0
	v_cvt_pk_bf16_f32 v111, v112, v113
	v_or_b32_e32 v112, v120, v158
	v_ashrrev_i32_e32 v113, 31, v112
	v_lshlrev_b64 v[112:113], 11, v[112:113]
	v_lshl_add_u64 v[112:113], v[144:145], 0, v[112:113]
	global_store_dwordx2 v[112:113], v[110:111], off
	s_nop 1
	v_mov_b32_e32 v110, v194
	v_mov_b32_e32 v111, v195
	v_lshlrev_b32_e32 v112, 16, v110
	v_and_b32_e32 v113, 0xffff0000, v110
	v_pk_fma_f32 v[106:107], v[14:15], v[112:113], v[106:107]
	s_nop 0
	v_pk_mul_f32 v[112:113], v[106:107], v[106:107]
	s_nop 0
	v_fmamk_f32 v110, v112, 0xbdd2d3e8, v178
	v_mul_f32_e32 v110, v106, v110
	v_exp_f32_e32 v110, v110
	s_nop 0
	v_add_f32_e32 v110, 1.0, v110
	v_rcp_f32_e32 v112, v110
	v_fmamk_f32 v110, v113, 0xbdd2d3e8, v178
	v_mul_f32_e32 v110, v107, v110
	v_exp_f32_e32 v110, v110
	s_nop 0
	v_add_f32_e32 v110, 1.0, v110
	v_rcp_f32_e32 v113, v110
	v_lshlrev_b32_e32 v110, 16, v111
	v_and_b32_e32 v111, 0xffff0000, v111
	v_pk_fma_f32 v[108:109], v[16:17], v[110:111], v[108:109]
	v_pk_mul_f32 v[106:107], v[106:107], v[112:113]
	v_pk_mul_f32 v[110:111], v[108:109], v[108:109]
	v_cvt_pk_bf16_f32 v106, v106, v107
	v_fmamk_f32 v107, v110, 0xbdd2d3e8, v178
	v_mul_f32_e32 v107, v108, v107
	v_exp_f32_e32 v107, v107
	s_nop 0
	v_add_f32_e32 v107, 1.0, v107
	v_rcp_f32_e32 v110, v107
	v_fmamk_f32 v107, v111, 0xbdd2d3e8, v178
	v_mul_f32_e32 v107, v109, v107
	v_exp_f32_e32 v107, v107
	s_nop 0
	v_add_f32_e32 v107, 1.0, v107
	v_rcp_f32_e32 v111, v107
	s_nop 0
	v_pk_mul_f32 v[108:109], v[108:109], v[110:111]
	s_nop 0
	v_cvt_pk_bf16_f32 v107, v108, v109
	v_or_b32_e32 v108, v120, v159
	v_ashrrev_i32_e32 v109, 31, v108
	v_lshlrev_b64 v[108:109], 11, v[108:109]
	v_lshl_add_u64 v[108:109], v[144:145], 0, v[108:109]
	global_store_dwordx2 v[108:109], v[106:107], off
	s_nop 1
	v_mov_b32_e32 v106, v196
	v_mov_b32_e32 v107, v197
	v_lshlrev_b32_e32 v108, 16, v106
	v_and_b32_e32 v109, 0xffff0000, v106
	v_pk_fma_f32 v[102:103], v[14:15], v[108:109], v[102:103]
	s_nop 0
	v_pk_mul_f32 v[108:109], v[102:103], v[102:103]
	s_nop 0
	v_fmamk_f32 v106, v108, 0xbdd2d3e8, v178
	v_mul_f32_e32 v106, v102, v106
	v_exp_f32_e32 v106, v106
	s_nop 0
	v_add_f32_e32 v106, 1.0, v106
	v_rcp_f32_e32 v108, v106
	v_fmamk_f32 v106, v109, 0xbdd2d3e8, v178
	v_mul_f32_e32 v106, v103, v106
	v_exp_f32_e32 v106, v106
	s_nop 0
	v_add_f32_e32 v106, 1.0, v106
	v_rcp_f32_e32 v109, v106
	v_lshlrev_b32_e32 v106, 16, v107
	v_and_b32_e32 v107, 0xffff0000, v107
	v_pk_fma_f32 v[104:105], v[16:17], v[106:107], v[104:105]
	v_pk_mul_f32 v[102:103], v[102:103], v[108:109]
	v_pk_mul_f32 v[106:107], v[104:105], v[104:105]
	v_cvt_pk_bf16_f32 v102, v102, v103
	v_fmamk_f32 v103, v106, 0xbdd2d3e8, v178
	v_mul_f32_e32 v103, v104, v103
	v_exp_f32_e32 v103, v103
	s_nop 0
	v_add_f32_e32 v103, 1.0, v103
	v_rcp_f32_e32 v106, v103
	v_fmamk_f32 v103, v107, 0xbdd2d3e8, v178
	v_mul_f32_e32 v103, v105, v103
	v_exp_f32_e32 v103, v103
	s_nop 0
	v_add_f32_e32 v103, 1.0, v103
	v_rcp_f32_e32 v107, v103
	s_nop 0
	v_pk_mul_f32 v[104:105], v[104:105], v[106:107]
	s_nop 0
	v_cvt_pk_bf16_f32 v103, v104, v105
	v_or_b32_e32 v104, v120, v160
	v_ashrrev_i32_e32 v105, 31, v104
	v_lshlrev_b64 v[104:105], 11, v[104:105]
	v_lshl_add_u64 v[104:105], v[144:145], 0, v[104:105]
	global_store_dwordx2 v[104:105], v[102:103], off
	v_add_u32_e32 v104, 32, v148
	v_ashrrev_i32_e32 v105, 31, v104
	v_lshlrev_b64 v[102:103], 9, v[104:105]
	v_lshl_add_u64 v[102:103], v[146:147], 0, v[102:103]
	v_lshlrev_b32_e32 v104, 4, v104
	s_nop 1
	v_mov_b32_e32 v106, v198
	v_mov_b32_e32 v107, v199
	v_lshlrev_b32_e32 v108, 16, v106
	v_and_b32_e32 v109, 0xffff0000, v106
	v_pk_fma_f32 v[98:99], v[14:15], v[108:109], v[98:99]
	v_lshlrev_b32_e32 v106, 16, v107
	v_pk_mul_f32 v[108:109], v[98:99], v[98:99]
	v_and_b32_e32 v107, 0xffff0000, v107
	v_fmamk_f32 v105, v108, 0xbdd2d3e8, v178
	v_mul_f32_e32 v105, v98, v105
	v_exp_f32_e32 v105, v105
	v_pk_fma_f32 v[100:101], v[16:17], v[106:107], v[100:101]
	v_add_f32_e32 v105, 1.0, v105
	v_rcp_f32_e32 v108, v105
	v_fmamk_f32 v105, v109, 0xbdd2d3e8, v178
	v_mul_f32_e32 v105, v99, v105
	v_exp_f32_e32 v105, v105
	v_pk_mul_f32 v[106:107], v[100:101], v[100:101]
	v_add_f32_e32 v105, 1.0, v105
	v_rcp_f32_e32 v109, v105
	s_nop 0
	v_pk_mul_f32 v[98:99], v[98:99], v[108:109]
	s_nop 0
	v_cvt_pk_bf16_f32 v98, v98, v99
	v_fmamk_f32 v99, v106, 0xbdd2d3e8, v178
	v_mul_f32_e32 v99, v100, v99
	v_exp_f32_e32 v99, v99
	s_nop 0
	v_add_f32_e32 v99, 1.0, v99
	v_rcp_f32_e32 v106, v99
	v_fmamk_f32 v99, v107, 0xbdd2d3e8, v178
	v_mul_f32_e32 v99, v101, v99
	v_exp_f32_e32 v99, v99
	s_nop 0
	v_add_f32_e32 v99, 1.0, v99
	v_rcp_f32_e32 v107, v99
	s_nop 0
	v_pk_mul_f32 v[100:101], v[100:101], v[106:107]
	s_nop 0
	v_cvt_pk_bf16_f32 v99, v100, v101
	v_or_b32_e32 v100, v104, v157
	v_ashrrev_i32_e32 v101, 31, v100
	v_lshlrev_b64 v[100:101], 11, v[100:101]
	v_lshl_add_u64 v[100:101], v[144:145], 0, v[100:101]
	global_store_dwordx2 v[100:101], v[98:99], off
	s_nop 1
	v_mov_b32_e32 v98, v200
	v_mov_b32_e32 v99, v201
	v_lshlrev_b32_e32 v100, 16, v98
	v_and_b32_e32 v101, 0xffff0000, v98
	v_pk_fma_f32 v[94:95], v[14:15], v[100:101], v[94:95]
	s_nop 0
	v_pk_mul_f32 v[100:101], v[94:95], v[94:95]
	s_nop 0
	v_fmamk_f32 v98, v100, 0xbdd2d3e8, v178
	v_mul_f32_e32 v98, v94, v98
	v_exp_f32_e32 v98, v98
	s_nop 0
	v_add_f32_e32 v98, 1.0, v98
	v_rcp_f32_e32 v100, v98
	v_fmamk_f32 v98, v101, 0xbdd2d3e8, v178
	v_mul_f32_e32 v98, v95, v98
	v_exp_f32_e32 v98, v98
	s_nop 0
	v_add_f32_e32 v98, 1.0, v98
	v_rcp_f32_e32 v101, v98
	v_lshlrev_b32_e32 v98, 16, v99
	v_and_b32_e32 v99, 0xffff0000, v99
	v_pk_fma_f32 v[96:97], v[16:17], v[98:99], v[96:97]
	v_pk_mul_f32 v[94:95], v[94:95], v[100:101]
	v_pk_mul_f32 v[98:99], v[96:97], v[96:97]
	v_cvt_pk_bf16_f32 v94, v94, v95
	v_fmamk_f32 v95, v98, 0xbdd2d3e8, v178
	v_mul_f32_e32 v95, v96, v95
	v_exp_f32_e32 v95, v95
	s_nop 0
	v_add_f32_e32 v95, 1.0, v95
	v_rcp_f32_e32 v98, v95
	v_fmamk_f32 v95, v99, 0xbdd2d3e8, v178
	v_mul_f32_e32 v95, v97, v95
	v_exp_f32_e32 v95, v95
	s_nop 0
	v_add_f32_e32 v95, 1.0, v95
	v_rcp_f32_e32 v99, v95
	s_nop 0
	v_pk_mul_f32 v[96:97], v[96:97], v[98:99]
	s_nop 0
	v_cvt_pk_bf16_f32 v95, v96, v97
	v_or_b32_e32 v96, v104, v158
	v_ashrrev_i32_e32 v97, 31, v96
	v_lshlrev_b64 v[96:97], 11, v[96:97]
	v_lshl_add_u64 v[96:97], v[144:145], 0, v[96:97]
	global_store_dwordx2 v[96:97], v[94:95], off
	s_nop 1
	v_mov_b32_e32 v94, v202
	v_mov_b32_e32 v95, v203
	v_lshlrev_b32_e32 v96, 16, v94
	v_and_b32_e32 v97, 0xffff0000, v94
	v_pk_fma_f32 v[90:91], v[14:15], v[96:97], v[90:91]
	s_nop 0
	v_pk_mul_f32 v[96:97], v[90:91], v[90:91]
	s_nop 0
	v_fmamk_f32 v94, v96, 0xbdd2d3e8, v178
	v_mul_f32_e32 v94, v90, v94
	v_exp_f32_e32 v94, v94
	s_nop 0
	v_add_f32_e32 v94, 1.0, v94
	v_rcp_f32_e32 v96, v94
	v_fmamk_f32 v94, v97, 0xbdd2d3e8, v178
	v_mul_f32_e32 v94, v91, v94
	v_exp_f32_e32 v94, v94
	s_nop 0
	v_add_f32_e32 v94, 1.0, v94
	v_rcp_f32_e32 v97, v94
	v_lshlrev_b32_e32 v94, 16, v95
	v_and_b32_e32 v95, 0xffff0000, v95
	v_pk_fma_f32 v[92:93], v[16:17], v[94:95], v[92:93]
	v_pk_mul_f32 v[90:91], v[90:91], v[96:97]
	v_pk_mul_f32 v[94:95], v[92:93], v[92:93]
	v_cvt_pk_bf16_f32 v90, v90, v91
	v_fmamk_f32 v91, v94, 0xbdd2d3e8, v178
	v_mul_f32_e32 v91, v92, v91
	v_exp_f32_e32 v91, v91
	s_nop 0
	v_add_f32_e32 v91, 1.0, v91
	v_rcp_f32_e32 v94, v91
	v_fmamk_f32 v91, v95, 0xbdd2d3e8, v178
	v_mul_f32_e32 v91, v93, v91
	v_exp_f32_e32 v91, v91
	s_nop 0
	v_add_f32_e32 v91, 1.0, v91
	v_rcp_f32_e32 v95, v91
	s_nop 0
	v_pk_mul_f32 v[92:93], v[92:93], v[94:95]
	s_nop 0
	v_cvt_pk_bf16_f32 v91, v92, v93
	v_or_b32_e32 v92, v104, v159
	v_ashrrev_i32_e32 v93, 31, v92
	v_lshlrev_b64 v[92:93], 11, v[92:93]
	v_lshl_add_u64 v[92:93], v[144:145], 0, v[92:93]
	global_store_dwordx2 v[92:93], v[90:91], off
	s_nop 1
	v_mov_b32_e32 v90, v204
	v_mov_b32_e32 v91, v205
	v_lshlrev_b32_e32 v92, 16, v90
	v_and_b32_e32 v93, 0xffff0000, v90
	v_pk_fma_f32 v[86:87], v[14:15], v[92:93], v[86:87]
	s_nop 0
	v_pk_mul_f32 v[92:93], v[86:87], v[86:87]
	s_nop 0
	v_fmamk_f32 v90, v92, 0xbdd2d3e8, v178
	v_mul_f32_e32 v90, v86, v90
	v_exp_f32_e32 v90, v90
	s_nop 0
	v_add_f32_e32 v90, 1.0, v90
	v_rcp_f32_e32 v92, v90
	v_fmamk_f32 v90, v93, 0xbdd2d3e8, v178
	v_mul_f32_e32 v90, v87, v90
	v_exp_f32_e32 v90, v90
	s_nop 0
	v_add_f32_e32 v90, 1.0, v90
	v_rcp_f32_e32 v93, v90
	v_lshlrev_b32_e32 v90, 16, v91
	v_and_b32_e32 v91, 0xffff0000, v91
	v_pk_fma_f32 v[88:89], v[16:17], v[90:91], v[88:89]
	v_pk_mul_f32 v[86:87], v[86:87], v[92:93]
	v_pk_mul_f32 v[90:91], v[88:89], v[88:89]
	v_cvt_pk_bf16_f32 v86, v86, v87
	v_fmamk_f32 v87, v90, 0xbdd2d3e8, v178
	v_mul_f32_e32 v87, v88, v87
	v_exp_f32_e32 v87, v87
	s_nop 0
	v_add_f32_e32 v87, 1.0, v87
	v_rcp_f32_e32 v90, v87
	v_fmamk_f32 v87, v91, 0xbdd2d3e8, v178
	v_mul_f32_e32 v87, v89, v87
	v_exp_f32_e32 v87, v87
	s_nop 0
	v_add_f32_e32 v87, 1.0, v87
	v_rcp_f32_e32 v91, v87
	s_nop 0
	v_pk_mul_f32 v[88:89], v[88:89], v[90:91]
	s_nop 0
	v_cvt_pk_bf16_f32 v87, v88, v89
	v_or_b32_e32 v88, v104, v160
	v_ashrrev_i32_e32 v89, 31, v88
	v_lshlrev_b64 v[88:89], 11, v[88:89]
	v_lshl_add_u64 v[88:89], v[144:145], 0, v[88:89]
	global_store_dwordx2 v[88:89], v[86:87], off
	v_add_u32_e32 v88, 48, v148
	v_ashrrev_i32_e32 v89, 31, v88
	v_lshlrev_b64 v[86:87], 9, v[88:89]
	v_lshl_add_u64 v[86:87], v[146:147], 0, v[86:87]
	v_lshlrev_b32_e32 v88, 4, v88
	s_nop 1
	v_mov_b32_e32 v90, v206
	v_mov_b32_e32 v91, v207
	v_lshlrev_b32_e32 v92, 16, v90
	v_and_b32_e32 v93, 0xffff0000, v90
	v_pk_fma_f32 v[82:83], v[14:15], v[92:93], v[82:83]
	v_lshlrev_b32_e32 v90, 16, v91
	v_pk_mul_f32 v[92:93], v[82:83], v[82:83]
	v_and_b32_e32 v91, 0xffff0000, v91
	v_fmamk_f32 v89, v92, 0xbdd2d3e8, v178
	v_mul_f32_e32 v89, v82, v89
	v_exp_f32_e32 v89, v89
	v_pk_fma_f32 v[84:85], v[16:17], v[90:91], v[84:85]
	v_add_f32_e32 v89, 1.0, v89
	v_rcp_f32_e32 v92, v89
	v_fmamk_f32 v89, v93, 0xbdd2d3e8, v178
	v_mul_f32_e32 v89, v83, v89
	v_exp_f32_e32 v89, v89
	v_pk_mul_f32 v[90:91], v[84:85], v[84:85]
	v_add_f32_e32 v89, 1.0, v89
	v_rcp_f32_e32 v93, v89
	s_nop 0
	v_pk_mul_f32 v[82:83], v[82:83], v[92:93]
	s_nop 0
	v_cvt_pk_bf16_f32 v82, v82, v83
	v_fmamk_f32 v83, v90, 0xbdd2d3e8, v178
	v_mul_f32_e32 v83, v84, v83
	v_exp_f32_e32 v83, v83
	s_nop 0
	v_add_f32_e32 v83, 1.0, v83
	v_rcp_f32_e32 v90, v83
	v_fmamk_f32 v83, v91, 0xbdd2d3e8, v178
	v_mul_f32_e32 v83, v85, v83
	v_exp_f32_e32 v83, v83
	s_nop 0
	v_add_f32_e32 v83, 1.0, v83
	v_rcp_f32_e32 v91, v83
	s_nop 0
	v_pk_mul_f32 v[84:85], v[84:85], v[90:91]
	s_nop 0
	v_cvt_pk_bf16_f32 v83, v84, v85
	v_or_b32_e32 v84, v88, v157
	v_ashrrev_i32_e32 v85, 31, v84
	v_lshlrev_b64 v[84:85], 11, v[84:85]
	v_lshl_add_u64 v[84:85], v[144:145], 0, v[84:85]
	global_store_dwordx2 v[84:85], v[82:83], off
	s_nop 1
	v_mov_b32_e32 v82, v208
	v_mov_b32_e32 v83, v209
	v_lshlrev_b32_e32 v84, 16, v82
	v_and_b32_e32 v85, 0xffff0000, v82
	v_pk_fma_f32 v[78:79], v[14:15], v[84:85], v[78:79]
	s_nop 0
	v_pk_mul_f32 v[84:85], v[78:79], v[78:79]
	s_nop 0
	v_fmamk_f32 v82, v84, 0xbdd2d3e8, v178
	v_mul_f32_e32 v82, v78, v82
	v_exp_f32_e32 v82, v82
	s_nop 0
	v_add_f32_e32 v82, 1.0, v82
	v_rcp_f32_e32 v84, v82
	v_fmamk_f32 v82, v85, 0xbdd2d3e8, v178
	v_mul_f32_e32 v82, v79, v82
	v_exp_f32_e32 v82, v82
	s_nop 0
	v_add_f32_e32 v82, 1.0, v82
	v_rcp_f32_e32 v85, v82
	v_lshlrev_b32_e32 v82, 16, v83
	v_and_b32_e32 v83, 0xffff0000, v83
	v_pk_fma_f32 v[80:81], v[16:17], v[82:83], v[80:81]
	v_pk_mul_f32 v[78:79], v[78:79], v[84:85]
	v_pk_mul_f32 v[82:83], v[80:81], v[80:81]
	v_cvt_pk_bf16_f32 v78, v78, v79
	v_fmamk_f32 v79, v82, 0xbdd2d3e8, v178
	v_mul_f32_e32 v79, v80, v79
	v_exp_f32_e32 v79, v79
	s_nop 0
	v_add_f32_e32 v79, 1.0, v79
	v_rcp_f32_e32 v82, v79
	v_fmamk_f32 v79, v83, 0xbdd2d3e8, v178
	v_mul_f32_e32 v79, v81, v79
	v_exp_f32_e32 v79, v79
	s_nop 0
	v_add_f32_e32 v79, 1.0, v79
	v_rcp_f32_e32 v83, v79
	s_nop 0
	v_pk_mul_f32 v[80:81], v[80:81], v[82:83]
	s_nop 0
	v_cvt_pk_bf16_f32 v79, v80, v81
	v_or_b32_e32 v80, v88, v158
	v_ashrrev_i32_e32 v81, 31, v80
	v_lshlrev_b64 v[80:81], 11, v[80:81]
	v_lshl_add_u64 v[80:81], v[144:145], 0, v[80:81]
	global_store_dwordx2 v[80:81], v[78:79], off
	s_nop 1
	v_mov_b32_e32 v78, v210
	v_mov_b32_e32 v79, v211
	v_lshlrev_b32_e32 v80, 16, v78
	v_and_b32_e32 v81, 0xffff0000, v78
	v_pk_fma_f32 v[74:75], v[14:15], v[80:81], v[74:75]
	s_nop 0
	v_pk_mul_f32 v[80:81], v[74:75], v[74:75]
	s_nop 0
	v_fmamk_f32 v78, v80, 0xbdd2d3e8, v178
	v_mul_f32_e32 v78, v74, v78
	v_exp_f32_e32 v78, v78
	s_nop 0
	v_add_f32_e32 v78, 1.0, v78
	v_rcp_f32_e32 v80, v78
	v_fmamk_f32 v78, v81, 0xbdd2d3e8, v178
	v_mul_f32_e32 v78, v75, v78
	v_exp_f32_e32 v78, v78
	s_nop 0
	v_add_f32_e32 v78, 1.0, v78
	v_rcp_f32_e32 v81, v78
	v_lshlrev_b32_e32 v78, 16, v79
	v_and_b32_e32 v79, 0xffff0000, v79
	v_pk_fma_f32 v[76:77], v[16:17], v[78:79], v[76:77]
	v_pk_mul_f32 v[74:75], v[74:75], v[80:81]
	v_pk_mul_f32 v[78:79], v[76:77], v[76:77]
	v_cvt_pk_bf16_f32 v74, v74, v75
	v_fmamk_f32 v75, v78, 0xbdd2d3e8, v178
	v_mul_f32_e32 v75, v76, v75
	v_exp_f32_e32 v75, v75
	s_nop 0
	v_add_f32_e32 v75, 1.0, v75
	v_rcp_f32_e32 v78, v75
	v_fmamk_f32 v75, v79, 0xbdd2d3e8, v178
	v_mul_f32_e32 v75, v77, v75
	v_exp_f32_e32 v75, v75
	s_nop 0
	v_add_f32_e32 v75, 1.0, v75
	v_rcp_f32_e32 v79, v75
	s_nop 0
	v_pk_mul_f32 v[76:77], v[76:77], v[78:79]
	s_nop 0
	v_cvt_pk_bf16_f32 v75, v76, v77
	v_or_b32_e32 v76, v88, v159
	v_ashrrev_i32_e32 v77, 31, v76
	v_lshlrev_b64 v[76:77], 11, v[76:77]
	v_lshl_add_u64 v[76:77], v[144:145], 0, v[76:77]
	global_store_dwordx2 v[76:77], v[74:75], off
	s_nop 1
	v_mov_b32_e32 v74, v212
	v_mov_b32_e32 v75, v213
	v_lshlrev_b32_e32 v76, 16, v74
	v_and_b32_e32 v77, 0xffff0000, v74
	v_pk_fma_f32 v[70:71], v[14:15], v[76:77], v[70:71]
	s_nop 0
	v_pk_mul_f32 v[76:77], v[70:71], v[70:71]
	s_nop 0
	v_fmamk_f32 v74, v76, 0xbdd2d3e8, v178
	v_mul_f32_e32 v74, v70, v74
	v_exp_f32_e32 v74, v74
	s_nop 0
	v_add_f32_e32 v74, 1.0, v74
	v_rcp_f32_e32 v76, v74
	v_fmamk_f32 v74, v77, 0xbdd2d3e8, v178
	v_mul_f32_e32 v74, v71, v74
	v_exp_f32_e32 v74, v74
	s_nop 0
	v_add_f32_e32 v74, 1.0, v74
	v_rcp_f32_e32 v77, v74
	v_lshlrev_b32_e32 v74, 16, v75
	v_and_b32_e32 v75, 0xffff0000, v75
	v_pk_fma_f32 v[72:73], v[16:17], v[74:75], v[72:73]
	v_pk_mul_f32 v[70:71], v[70:71], v[76:77]
	v_pk_mul_f32 v[74:75], v[72:73], v[72:73]
	v_cvt_pk_bf16_f32 v70, v70, v71
	v_fmamk_f32 v71, v74, 0xbdd2d3e8, v178
	v_mul_f32_e32 v71, v72, v71
	v_exp_f32_e32 v71, v71
	s_nop 0
	v_add_f32_e32 v71, 1.0, v71
	v_rcp_f32_e32 v74, v71
	v_fmamk_f32 v71, v75, 0xbdd2d3e8, v178
	v_mul_f32_e32 v71, v73, v71
	v_exp_f32_e32 v71, v71
	s_nop 0
	v_add_f32_e32 v71, 1.0, v71
	v_rcp_f32_e32 v75, v71
	s_nop 0
	v_pk_mul_f32 v[72:73], v[72:73], v[74:75]
	s_nop 0
	v_cvt_pk_bf16_f32 v71, v72, v73
	v_or_b32_e32 v72, v88, v160
	v_ashrrev_i32_e32 v73, 31, v72
	v_lshlrev_b64 v[72:73], 11, v[72:73]
	v_lshl_add_u64 v[72:73], v[144:145], 0, v[72:73]
	global_store_dwordx2 v[72:73], v[70:71], off
	v_add_u32_e32 v72, 64, v148
	v_ashrrev_i32_e32 v73, 31, v72
	v_lshlrev_b64 v[70:71], 9, v[72:73]
	v_lshl_add_u64 v[70:71], v[146:147], 0, v[70:71]
	v_lshlrev_b32_e32 v72, 4, v72
	s_nop 1
	v_mov_b32_e32 v74, v214
	v_mov_b32_e32 v75, v215
	v_lshlrev_b32_e32 v76, 16, v74
	v_and_b32_e32 v77, 0xffff0000, v74
	v_pk_fma_f32 v[66:67], v[14:15], v[76:77], v[66:67]
	v_lshlrev_b32_e32 v74, 16, v75
	v_pk_mul_f32 v[76:77], v[66:67], v[66:67]
	v_and_b32_e32 v75, 0xffff0000, v75
	v_fmamk_f32 v73, v76, 0xbdd2d3e8, v178
	v_mul_f32_e32 v73, v66, v73
	v_exp_f32_e32 v73, v73
	v_pk_fma_f32 v[68:69], v[16:17], v[74:75], v[68:69]
	v_add_f32_e32 v73, 1.0, v73
	v_rcp_f32_e32 v76, v73
	v_fmamk_f32 v73, v77, 0xbdd2d3e8, v178
	v_mul_f32_e32 v73, v67, v73
	v_exp_f32_e32 v73, v73
	v_pk_mul_f32 v[74:75], v[68:69], v[68:69]
	v_add_f32_e32 v73, 1.0, v73
	v_rcp_f32_e32 v77, v73
	s_nop 0
	v_pk_mul_f32 v[66:67], v[66:67], v[76:77]
	s_nop 0
	v_cvt_pk_bf16_f32 v66, v66, v67
	v_fmamk_f32 v67, v74, 0xbdd2d3e8, v178
	v_mul_f32_e32 v67, v68, v67
	v_exp_f32_e32 v67, v67
	s_nop 0
	v_add_f32_e32 v67, 1.0, v67
	v_rcp_f32_e32 v74, v67
	v_fmamk_f32 v67, v75, 0xbdd2d3e8, v178
	v_mul_f32_e32 v67, v69, v67
	v_exp_f32_e32 v67, v67
	s_nop 0
	v_add_f32_e32 v67, 1.0, v67
	v_rcp_f32_e32 v75, v67
	s_nop 0
	v_pk_mul_f32 v[68:69], v[68:69], v[74:75]
	s_nop 0
	v_cvt_pk_bf16_f32 v67, v68, v69
	v_or_b32_e32 v68, v72, v157
	v_ashrrev_i32_e32 v69, 31, v68
	v_lshlrev_b64 v[68:69], 11, v[68:69]
	v_lshl_add_u64 v[68:69], v[144:145], 0, v[68:69]
	global_store_dwordx2 v[68:69], v[66:67], off
	s_nop 1
	v_mov_b32_e32 v66, v216
	v_mov_b32_e32 v67, v217
	v_lshlrev_b32_e32 v68, 16, v66
	v_and_b32_e32 v69, 0xffff0000, v66
	v_pk_fma_f32 v[62:63], v[14:15], v[68:69], v[62:63]
	s_nop 0
	v_pk_mul_f32 v[68:69], v[62:63], v[62:63]
	s_nop 0
	v_fmamk_f32 v66, v68, 0xbdd2d3e8, v178
	v_mul_f32_e32 v66, v62, v66
	v_exp_f32_e32 v66, v66
	s_nop 0
	v_add_f32_e32 v66, 1.0, v66
	v_rcp_f32_e32 v68, v66
	v_fmamk_f32 v66, v69, 0xbdd2d3e8, v178
	v_mul_f32_e32 v66, v63, v66
	v_exp_f32_e32 v66, v66
	s_nop 0
	v_add_f32_e32 v66, 1.0, v66
	v_rcp_f32_e32 v69, v66
	v_lshlrev_b32_e32 v66, 16, v67
	v_and_b32_e32 v67, 0xffff0000, v67
	v_pk_fma_f32 v[64:65], v[16:17], v[66:67], v[64:65]
	v_pk_mul_f32 v[62:63], v[62:63], v[68:69]
	v_pk_mul_f32 v[66:67], v[64:65], v[64:65]
	v_cvt_pk_bf16_f32 v62, v62, v63
	v_fmamk_f32 v63, v66, 0xbdd2d3e8, v178
	v_mul_f32_e32 v63, v64, v63
	v_exp_f32_e32 v63, v63
	s_nop 0
	v_add_f32_e32 v63, 1.0, v63
	v_rcp_f32_e32 v66, v63
	v_fmamk_f32 v63, v67, 0xbdd2d3e8, v178
	v_mul_f32_e32 v63, v65, v63
	v_exp_f32_e32 v63, v63
	s_nop 0
	v_add_f32_e32 v63, 1.0, v63
	v_rcp_f32_e32 v67, v63
	s_nop 0
	v_pk_mul_f32 v[64:65], v[64:65], v[66:67]
	s_nop 0
	v_cvt_pk_bf16_f32 v63, v64, v65
	v_or_b32_e32 v64, v72, v158
	v_ashrrev_i32_e32 v65, 31, v64
	v_lshlrev_b64 v[64:65], 11, v[64:65]
	v_lshl_add_u64 v[64:65], v[144:145], 0, v[64:65]
	global_store_dwordx2 v[64:65], v[62:63], off
	s_nop 1
	v_mov_b32_e32 v62, v222
	v_mov_b32_e32 v63, v223
	v_lshlrev_b32_e32 v64, 16, v62
	v_and_b32_e32 v65, 0xffff0000, v62
	v_pk_fma_f32 v[58:59], v[14:15], v[64:65], v[58:59]
	s_nop 0
	v_pk_mul_f32 v[64:65], v[58:59], v[58:59]
	s_nop 0
	v_fmamk_f32 v62, v64, 0xbdd2d3e8, v178
	v_mul_f32_e32 v62, v58, v62
	v_exp_f32_e32 v62, v62
	s_nop 0
	v_add_f32_e32 v62, 1.0, v62
	v_rcp_f32_e32 v64, v62
	v_fmamk_f32 v62, v65, 0xbdd2d3e8, v178
	v_mul_f32_e32 v62, v59, v62
	v_exp_f32_e32 v62, v62
	s_nop 0
	v_add_f32_e32 v62, 1.0, v62
	v_rcp_f32_e32 v65, v62
	v_lshlrev_b32_e32 v62, 16, v63
	v_and_b32_e32 v63, 0xffff0000, v63
	v_pk_fma_f32 v[60:61], v[16:17], v[62:63], v[60:61]
	v_pk_mul_f32 v[58:59], v[58:59], v[64:65]
	v_pk_mul_f32 v[62:63], v[60:61], v[60:61]
	v_cvt_pk_bf16_f32 v58, v58, v59
	v_fmamk_f32 v59, v62, 0xbdd2d3e8, v178
	v_mul_f32_e32 v59, v60, v59
	v_exp_f32_e32 v59, v59
	s_nop 0
	v_add_f32_e32 v59, 1.0, v59
	v_rcp_f32_e32 v62, v59
	v_fmamk_f32 v59, v63, 0xbdd2d3e8, v178
	v_mul_f32_e32 v59, v61, v59
	v_exp_f32_e32 v59, v59
	s_nop 0
	v_add_f32_e32 v59, 1.0, v59
	v_rcp_f32_e32 v63, v59
	s_nop 0
	v_pk_mul_f32 v[60:61], v[60:61], v[62:63]
	s_nop 0
	v_cvt_pk_bf16_f32 v59, v60, v61
	v_or_b32_e32 v60, v72, v159
	v_ashrrev_i32_e32 v61, 31, v60
	v_lshlrev_b64 v[60:61], 11, v[60:61]
	v_lshl_add_u64 v[60:61], v[144:145], 0, v[60:61]
	global_store_dwordx2 v[60:61], v[58:59], off
	s_nop 1
	v_mov_b32_e32 v58, v224
	v_mov_b32_e32 v59, v225
	v_lshlrev_b32_e32 v60, 16, v58
	v_and_b32_e32 v61, 0xffff0000, v58
	v_pk_fma_f32 v[54:55], v[14:15], v[60:61], v[54:55]
	s_nop 0
	v_pk_mul_f32 v[60:61], v[54:55], v[54:55]
	s_nop 0
	v_fmamk_f32 v58, v60, 0xbdd2d3e8, v178
	v_mul_f32_e32 v58, v54, v58
	v_exp_f32_e32 v58, v58
	s_nop 0
	v_add_f32_e32 v58, 1.0, v58
	v_rcp_f32_e32 v60, v58
	v_fmamk_f32 v58, v61, 0xbdd2d3e8, v178
	v_mul_f32_e32 v58, v55, v58
	v_exp_f32_e32 v58, v58
	s_nop 0
	v_add_f32_e32 v58, 1.0, v58
	v_rcp_f32_e32 v61, v58
	v_lshlrev_b32_e32 v58, 16, v59
	v_and_b32_e32 v59, 0xffff0000, v59
	v_pk_fma_f32 v[56:57], v[16:17], v[58:59], v[56:57]
	v_pk_mul_f32 v[54:55], v[54:55], v[60:61]
	v_pk_mul_f32 v[58:59], v[56:57], v[56:57]
	v_cvt_pk_bf16_f32 v54, v54, v55
	v_fmamk_f32 v55, v58, 0xbdd2d3e8, v178
	v_mul_f32_e32 v55, v56, v55
	v_exp_f32_e32 v55, v55
	s_nop 0
	v_add_f32_e32 v55, 1.0, v55
	v_rcp_f32_e32 v58, v55
	v_fmamk_f32 v55, v59, 0xbdd2d3e8, v178
	v_mul_f32_e32 v55, v57, v55
	v_exp_f32_e32 v55, v55
	s_nop 0
	v_add_f32_e32 v55, 1.0, v55
	v_rcp_f32_e32 v59, v55
	s_nop 0
	v_pk_mul_f32 v[56:57], v[56:57], v[58:59]
	s_nop 0
	v_cvt_pk_bf16_f32 v55, v56, v57
	v_or_b32_e32 v56, v72, v160
	v_ashrrev_i32_e32 v57, 31, v56
	v_lshlrev_b64 v[56:57], 11, v[56:57]
	v_lshl_add_u64 v[56:57], v[144:145], 0, v[56:57]
	global_store_dwordx2 v[56:57], v[54:55], off
	v_add_u32_e32 v56, 0x50, v148
	v_ashrrev_i32_e32 v57, 31, v56
	v_lshlrev_b64 v[54:55], 9, v[56:57]
	v_lshl_add_u64 v[54:55], v[146:147], 0, v[54:55]
	v_lshlrev_b32_e32 v56, 4, v56
	s_nop 1
	v_mov_b32_e32 v58, v226
	v_mov_b32_e32 v59, v227
	v_lshlrev_b32_e32 v60, 16, v58
	v_and_b32_e32 v61, 0xffff0000, v58
	v_pk_fma_f32 v[50:51], v[14:15], v[60:61], v[50:51]
	v_lshlrev_b32_e32 v58, 16, v59
	v_pk_mul_f32 v[60:61], v[50:51], v[50:51]
	v_and_b32_e32 v59, 0xffff0000, v59
	v_fmamk_f32 v57, v60, 0xbdd2d3e8, v178
	v_mul_f32_e32 v57, v50, v57
	v_exp_f32_e32 v57, v57
	v_pk_fma_f32 v[52:53], v[16:17], v[58:59], v[52:53]
	v_add_f32_e32 v57, 1.0, v57
	v_rcp_f32_e32 v60, v57
	v_fmamk_f32 v57, v61, 0xbdd2d3e8, v178
	v_mul_f32_e32 v57, v51, v57
	v_exp_f32_e32 v57, v57
	v_pk_mul_f32 v[58:59], v[52:53], v[52:53]
	v_add_f32_e32 v57, 1.0, v57
	v_rcp_f32_e32 v61, v57
	s_nop 0
	v_pk_mul_f32 v[50:51], v[50:51], v[60:61]
	s_nop 0
	v_cvt_pk_bf16_f32 v50, v50, v51
	v_fmamk_f32 v51, v58, 0xbdd2d3e8, v178
	v_mul_f32_e32 v51, v52, v51
	v_exp_f32_e32 v51, v51
	s_nop 0
	v_add_f32_e32 v51, 1.0, v51
	v_rcp_f32_e32 v58, v51
	v_fmamk_f32 v51, v59, 0xbdd2d3e8, v178
	v_mul_f32_e32 v51, v53, v51
	v_exp_f32_e32 v51, v51
	s_nop 0
	v_add_f32_e32 v51, 1.0, v51
	v_rcp_f32_e32 v59, v51
	s_nop 0
	v_pk_mul_f32 v[52:53], v[52:53], v[58:59]
	s_nop 0
	v_cvt_pk_bf16_f32 v51, v52, v53
	v_or_b32_e32 v52, v56, v157
	v_ashrrev_i32_e32 v53, 31, v52
	v_lshlrev_b64 v[52:53], 11, v[52:53]
	v_lshl_add_u64 v[52:53], v[144:145], 0, v[52:53]
	global_store_dwordx2 v[52:53], v[50:51], off
	s_nop 1
	v_mov_b32_e32 v50, v228
	v_mov_b32_e32 v51, v229
	v_lshlrev_b32_e32 v52, 16, v50
	v_and_b32_e32 v53, 0xffff0000, v50
	v_pk_fma_f32 v[46:47], v[14:15], v[52:53], v[46:47]
	s_nop 0
	v_pk_mul_f32 v[52:53], v[46:47], v[46:47]
	s_nop 0
	v_fmamk_f32 v50, v52, 0xbdd2d3e8, v178
	v_mul_f32_e32 v50, v46, v50
	v_exp_f32_e32 v50, v50
	s_nop 0
	v_add_f32_e32 v50, 1.0, v50
	v_rcp_f32_e32 v52, v50
	v_fmamk_f32 v50, v53, 0xbdd2d3e8, v178
	v_mul_f32_e32 v50, v47, v50
	v_exp_f32_e32 v50, v50
	s_nop 0
	v_add_f32_e32 v50, 1.0, v50
	v_rcp_f32_e32 v53, v50
	v_lshlrev_b32_e32 v50, 16, v51
	v_and_b32_e32 v51, 0xffff0000, v51
	v_pk_fma_f32 v[48:49], v[16:17], v[50:51], v[48:49]
	v_pk_mul_f32 v[46:47], v[46:47], v[52:53]
	v_pk_mul_f32 v[50:51], v[48:49], v[48:49]
	v_cvt_pk_bf16_f32 v46, v46, v47
	v_fmamk_f32 v47, v50, 0xbdd2d3e8, v178
	v_mul_f32_e32 v47, v48, v47
	v_exp_f32_e32 v47, v47
	s_nop 0
	v_add_f32_e32 v47, 1.0, v47
	v_rcp_f32_e32 v50, v47
	v_fmamk_f32 v47, v51, 0xbdd2d3e8, v178
	v_mul_f32_e32 v47, v49, v47
	v_exp_f32_e32 v47, v47
	s_nop 0
	v_add_f32_e32 v47, 1.0, v47
	v_rcp_f32_e32 v51, v47
	s_nop 0
	v_pk_mul_f32 v[48:49], v[48:49], v[50:51]
	s_nop 0
	v_cvt_pk_bf16_f32 v47, v48, v49
	v_or_b32_e32 v48, v56, v158
	v_ashrrev_i32_e32 v49, 31, v48
	v_lshlrev_b64 v[48:49], 11, v[48:49]
	v_lshl_add_u64 v[48:49], v[144:145], 0, v[48:49]
	global_store_dwordx2 v[48:49], v[46:47], off
	s_nop 1
	v_mov_b32_e32 v46, v230
	v_mov_b32_e32 v47, v231
	v_lshlrev_b32_e32 v48, 16, v46
	v_and_b32_e32 v49, 0xffff0000, v46
	v_pk_fma_f32 v[42:43], v[14:15], v[48:49], v[42:43]
	s_nop 0
	v_pk_mul_f32 v[48:49], v[42:43], v[42:43]
	s_nop 0
	v_fmamk_f32 v46, v48, 0xbdd2d3e8, v178
	v_mul_f32_e32 v46, v42, v46
	v_exp_f32_e32 v46, v46
	s_nop 0
	v_add_f32_e32 v46, 1.0, v46
	v_rcp_f32_e32 v48, v46
	v_fmamk_f32 v46, v49, 0xbdd2d3e8, v178
	v_mul_f32_e32 v46, v43, v46
	v_exp_f32_e32 v46, v46
	s_nop 0
	v_add_f32_e32 v46, 1.0, v46
	v_rcp_f32_e32 v49, v46
	v_lshlrev_b32_e32 v46, 16, v47
	v_and_b32_e32 v47, 0xffff0000, v47
	v_pk_fma_f32 v[44:45], v[16:17], v[46:47], v[44:45]
	v_pk_mul_f32 v[42:43], v[42:43], v[48:49]
	v_pk_mul_f32 v[46:47], v[44:45], v[44:45]
	v_cvt_pk_bf16_f32 v42, v42, v43
	v_fmamk_f32 v43, v46, 0xbdd2d3e8, v178
	v_mul_f32_e32 v43, v44, v43
	v_exp_f32_e32 v43, v43
	s_nop 0
	v_add_f32_e32 v43, 1.0, v43
	v_rcp_f32_e32 v46, v43
	v_fmamk_f32 v43, v47, 0xbdd2d3e8, v178
	v_mul_f32_e32 v43, v45, v43
	v_exp_f32_e32 v43, v43
	s_nop 0
	v_add_f32_e32 v43, 1.0, v43
	v_rcp_f32_e32 v47, v43
	s_nop 0
	v_pk_mul_f32 v[44:45], v[44:45], v[46:47]
	s_nop 0
	v_cvt_pk_bf16_f32 v43, v44, v45
	v_or_b32_e32 v44, v56, v159
	v_ashrrev_i32_e32 v45, 31, v44
	v_lshlrev_b64 v[44:45], 11, v[44:45]
	v_lshl_add_u64 v[44:45], v[144:145], 0, v[44:45]
	global_store_dwordx2 v[44:45], v[42:43], off
	s_nop 1
	v_mov_b32_e32 v42, v232
	v_mov_b32_e32 v43, v233
	v_lshlrev_b32_e32 v44, 16, v42
	v_and_b32_e32 v45, 0xffff0000, v42
	v_pk_fma_f32 v[38:39], v[14:15], v[44:45], v[38:39]
	s_nop 0
	v_pk_mul_f32 v[44:45], v[38:39], v[38:39]
	s_nop 0
	v_fmamk_f32 v42, v44, 0xbdd2d3e8, v178
	v_mul_f32_e32 v42, v38, v42
	v_exp_f32_e32 v42, v42
	s_nop 0
	v_add_f32_e32 v42, 1.0, v42
	v_rcp_f32_e32 v44, v42
	v_fmamk_f32 v42, v45, 0xbdd2d3e8, v178
	v_mul_f32_e32 v42, v39, v42
	v_exp_f32_e32 v42, v42
	s_nop 0
	v_add_f32_e32 v42, 1.0, v42
	v_rcp_f32_e32 v45, v42
	v_lshlrev_b32_e32 v42, 16, v43
	v_and_b32_e32 v43, 0xffff0000, v43
	v_pk_fma_f32 v[40:41], v[16:17], v[42:43], v[40:41]
	v_pk_mul_f32 v[38:39], v[38:39], v[44:45]
	v_pk_mul_f32 v[42:43], v[40:41], v[40:41]
	v_cvt_pk_bf16_f32 v38, v38, v39
	v_fmamk_f32 v39, v42, 0xbdd2d3e8, v178
	v_mul_f32_e32 v39, v40, v39
	v_exp_f32_e32 v39, v39
	s_nop 0
	v_add_f32_e32 v39, 1.0, v39
	v_rcp_f32_e32 v42, v39
	v_fmamk_f32 v39, v43, 0xbdd2d3e8, v178
	v_mul_f32_e32 v39, v41, v39
	v_exp_f32_e32 v39, v39
	s_nop 0
	v_add_f32_e32 v39, 1.0, v39
	v_rcp_f32_e32 v43, v39
	s_nop 0
	v_pk_mul_f32 v[40:41], v[40:41], v[42:43]
	s_nop 0
	v_cvt_pk_bf16_f32 v39, v40, v41
	v_or_b32_e32 v40, v56, v160
	v_ashrrev_i32_e32 v41, 31, v40
	v_lshlrev_b64 v[40:41], 11, v[40:41]
	v_lshl_add_u64 v[40:41], v[144:145], 0, v[40:41]
	global_store_dwordx2 v[40:41], v[38:39], off
	v_add_u32_e32 v40, 0x60, v148
	v_ashrrev_i32_e32 v41, 31, v40
	v_lshlrev_b64 v[38:39], 9, v[40:41]
	v_lshl_add_u64 v[38:39], v[146:147], 0, v[38:39]
	v_lshlrev_b32_e32 v40, 4, v40
	s_nop 1
	v_mov_b32_e32 v42, v234
	v_mov_b32_e32 v43, v235
	v_lshlrev_b32_e32 v44, 16, v42
	v_and_b32_e32 v45, 0xffff0000, v42
	v_pk_fma_f32 v[34:35], v[14:15], v[44:45], v[34:35]
	v_lshlrev_b32_e32 v42, 16, v43
	v_pk_mul_f32 v[44:45], v[34:35], v[34:35]
	v_and_b32_e32 v43, 0xffff0000, v43
	v_fmamk_f32 v41, v44, 0xbdd2d3e8, v178
	v_mul_f32_e32 v41, v34, v41
	v_exp_f32_e32 v41, v41
	v_pk_fma_f32 v[36:37], v[16:17], v[42:43], v[36:37]
	v_add_f32_e32 v41, 1.0, v41
	v_rcp_f32_e32 v44, v41
	v_fmamk_f32 v41, v45, 0xbdd2d3e8, v178
	v_mul_f32_e32 v41, v35, v41
	v_exp_f32_e32 v41, v41
	v_pk_mul_f32 v[42:43], v[36:37], v[36:37]
	v_add_f32_e32 v41, 1.0, v41
	v_rcp_f32_e32 v45, v41
	s_nop 0
	v_pk_mul_f32 v[34:35], v[34:35], v[44:45]
	s_nop 0
	v_cvt_pk_bf16_f32 v34, v34, v35
	v_fmamk_f32 v35, v42, 0xbdd2d3e8, v178
	v_mul_f32_e32 v35, v36, v35
	v_exp_f32_e32 v35, v35
	s_nop 0
	v_add_f32_e32 v35, 1.0, v35
	v_rcp_f32_e32 v42, v35
	v_fmamk_f32 v35, v43, 0xbdd2d3e8, v178
	v_mul_f32_e32 v35, v37, v35
	v_exp_f32_e32 v35, v35
	s_nop 0
	v_add_f32_e32 v35, 1.0, v35
	v_rcp_f32_e32 v43, v35
	s_nop 0
	v_pk_mul_f32 v[36:37], v[36:37], v[42:43]
	s_nop 0
	v_cvt_pk_bf16_f32 v35, v36, v37
	v_or_b32_e32 v36, v40, v157
	v_ashrrev_i32_e32 v37, 31, v36
	v_lshlrev_b64 v[36:37], 11, v[36:37]
	v_lshl_add_u64 v[36:37], v[144:145], 0, v[36:37]
	global_store_dwordx2 v[36:37], v[34:35], off
	s_nop 1
	v_mov_b32_e32 v34, v236
	v_mov_b32_e32 v35, v237
	v_lshlrev_b32_e32 v36, 16, v34
	v_and_b32_e32 v37, 0xffff0000, v34
	v_pk_fma_f32 v[30:31], v[14:15], v[36:37], v[30:31]
	s_nop 0
	v_pk_mul_f32 v[36:37], v[30:31], v[30:31]
	s_nop 0
	v_fmamk_f32 v34, v36, 0xbdd2d3e8, v178
	v_mul_f32_e32 v34, v30, v34
	v_exp_f32_e32 v34, v34
	s_nop 0
	v_add_f32_e32 v34, 1.0, v34
	v_rcp_f32_e32 v36, v34
	v_fmamk_f32 v34, v37, 0xbdd2d3e8, v178
	v_mul_f32_e32 v34, v31, v34
	v_exp_f32_e32 v34, v34
	s_nop 0
	v_add_f32_e32 v34, 1.0, v34
	v_rcp_f32_e32 v37, v34
	v_lshlrev_b32_e32 v34, 16, v35
	v_and_b32_e32 v35, 0xffff0000, v35
	v_pk_fma_f32 v[32:33], v[16:17], v[34:35], v[32:33]
	v_pk_mul_f32 v[30:31], v[30:31], v[36:37]
	v_pk_mul_f32 v[34:35], v[32:33], v[32:33]
	v_cvt_pk_bf16_f32 v30, v30, v31
	v_fmamk_f32 v31, v34, 0xbdd2d3e8, v178
	v_mul_f32_e32 v31, v32, v31
	v_exp_f32_e32 v31, v31
	s_nop 0
	v_add_f32_e32 v31, 1.0, v31
	v_rcp_f32_e32 v34, v31
	v_fmamk_f32 v31, v35, 0xbdd2d3e8, v178
	v_mul_f32_e32 v31, v33, v31
	v_exp_f32_e32 v31, v31
	s_nop 0
	v_add_f32_e32 v31, 1.0, v31
	v_rcp_f32_e32 v35, v31
	s_nop 0
	v_pk_mul_f32 v[32:33], v[32:33], v[34:35]
	s_nop 0
	v_cvt_pk_bf16_f32 v31, v32, v33
	v_or_b32_e32 v32, v40, v158
	v_ashrrev_i32_e32 v33, 31, v32
	v_lshlrev_b64 v[32:33], 11, v[32:33]
	v_lshl_add_u64 v[32:33], v[144:145], 0, v[32:33]
	global_store_dwordx2 v[32:33], v[30:31], off
	s_nop 1
	v_mov_b32_e32 v30, v238
	v_mov_b32_e32 v31, v239
	v_lshlrev_b32_e32 v32, 16, v30
	v_and_b32_e32 v33, 0xffff0000, v30
	v_pk_fma_f32 v[26:27], v[14:15], v[32:33], v[26:27]
	s_nop 0
	v_pk_mul_f32 v[32:33], v[26:27], v[26:27]
	s_nop 0
	v_fmamk_f32 v30, v32, 0xbdd2d3e8, v178
	v_mul_f32_e32 v30, v26, v30
	v_exp_f32_e32 v30, v30
	s_nop 0
	v_add_f32_e32 v30, 1.0, v30
	v_rcp_f32_e32 v32, v30
	v_fmamk_f32 v30, v33, 0xbdd2d3e8, v178
	v_mul_f32_e32 v30, v27, v30
	v_exp_f32_e32 v30, v30
	s_nop 0
	v_add_f32_e32 v30, 1.0, v30
	v_rcp_f32_e32 v33, v30
	v_lshlrev_b32_e32 v30, 16, v31
	v_and_b32_e32 v31, 0xffff0000, v31
	v_pk_fma_f32 v[28:29], v[16:17], v[30:31], v[28:29]
	v_pk_mul_f32 v[26:27], v[26:27], v[32:33]
	v_pk_mul_f32 v[30:31], v[28:29], v[28:29]
	v_cvt_pk_bf16_f32 v26, v26, v27
	v_fmamk_f32 v27, v30, 0xbdd2d3e8, v178
	v_mul_f32_e32 v27, v28, v27
	v_exp_f32_e32 v27, v27
	s_nop 0
	v_add_f32_e32 v27, 1.0, v27
	v_rcp_f32_e32 v30, v27
	v_fmamk_f32 v27, v31, 0xbdd2d3e8, v178
	v_mul_f32_e32 v27, v29, v27
	v_exp_f32_e32 v27, v27
	s_nop 0
	v_add_f32_e32 v27, 1.0, v27
	v_rcp_f32_e32 v31, v27
	s_nop 0
	v_pk_mul_f32 v[28:29], v[28:29], v[30:31]
	s_nop 0
	v_cvt_pk_bf16_f32 v27, v28, v29
	v_or_b32_e32 v28, v40, v159
	v_ashrrev_i32_e32 v29, 31, v28
	v_lshlrev_b64 v[28:29], 11, v[28:29]
	v_lshl_add_u64 v[28:29], v[144:145], 0, v[28:29]
	global_store_dwordx2 v[28:29], v[26:27], off
	s_nop 1
	v_mov_b32_e32 v26, v240
	v_mov_b32_e32 v27, v241
	v_lshlrev_b32_e32 v28, 16, v26
	v_and_b32_e32 v29, 0xffff0000, v26
	v_pk_fma_f32 v[22:23], v[14:15], v[28:29], v[22:23]
	s_nop 0
	v_pk_mul_f32 v[28:29], v[22:23], v[22:23]
	s_nop 0
	v_fmamk_f32 v26, v28, 0xbdd2d3e8, v178
	v_mul_f32_e32 v26, v22, v26
	v_exp_f32_e32 v26, v26
	s_nop 0
	v_add_f32_e32 v26, 1.0, v26
	v_rcp_f32_e32 v28, v26
	v_fmamk_f32 v26, v29, 0xbdd2d3e8, v178
	v_mul_f32_e32 v26, v23, v26
	v_exp_f32_e32 v26, v26
	s_nop 0
	v_add_f32_e32 v26, 1.0, v26
	v_rcp_f32_e32 v29, v26
	v_lshlrev_b32_e32 v26, 16, v27
	v_and_b32_e32 v27, 0xffff0000, v27
	v_pk_fma_f32 v[24:25], v[16:17], v[26:27], v[24:25]
	v_pk_mul_f32 v[22:23], v[22:23], v[28:29]
	v_pk_mul_f32 v[26:27], v[24:25], v[24:25]
	v_cvt_pk_bf16_f32 v22, v22, v23
	v_fmamk_f32 v23, v26, 0xbdd2d3e8, v178
	v_mul_f32_e32 v23, v24, v23
	v_exp_f32_e32 v23, v23
	s_nop 0
	v_add_f32_e32 v23, 1.0, v23
	v_rcp_f32_e32 v26, v23
	v_fmamk_f32 v23, v27, 0xbdd2d3e8, v178
	v_mul_f32_e32 v23, v25, v23
	v_exp_f32_e32 v23, v23
	s_nop 0
	v_add_f32_e32 v23, 1.0, v23
	v_rcp_f32_e32 v27, v23
	s_nop 0
	v_pk_mul_f32 v[24:25], v[24:25], v[26:27]
	s_nop 0
	v_cvt_pk_bf16_f32 v23, v24, v25
	v_or_b32_e32 v24, v40, v160
	v_ashrrev_i32_e32 v25, 31, v24
	v_lshlrev_b64 v[24:25], 11, v[24:25]
	v_lshl_add_u64 v[24:25], v[144:145], 0, v[24:25]
	global_store_dwordx2 v[24:25], v[22:23], off
	v_add_u32_e32 v24, 0x70, v148
	v_ashrrev_i32_e32 v25, 31, v24
	v_lshlrev_b64 v[22:23], 9, v[24:25]
	v_lshl_add_u64 v[22:23], v[146:147], 0, v[22:23]
	v_lshlrev_b32_e32 v24, 4, v24
	s_nop 1
	v_mov_b32_e32 v26, v242
	v_mov_b32_e32 v27, v243
	v_lshlrev_b32_e32 v28, 16, v26
	v_and_b32_e32 v29, 0xffff0000, v26
	v_pk_fma_f32 v[18:19], v[14:15], v[28:29], v[18:19]
	v_lshlrev_b32_e32 v26, 16, v27
	v_pk_mul_f32 v[28:29], v[18:19], v[18:19]
	v_and_b32_e32 v27, 0xffff0000, v27
	v_fmamk_f32 v25, v28, 0xbdd2d3e8, v178
	v_mul_f32_e32 v25, v18, v25
	v_exp_f32_e32 v25, v25
	v_pk_fma_f32 v[20:21], v[16:17], v[26:27], v[20:21]
	v_add_f32_e32 v25, 1.0, v25
	v_rcp_f32_e32 v28, v25
	v_fmamk_f32 v25, v29, 0xbdd2d3e8, v178
	v_mul_f32_e32 v25, v19, v25
	v_exp_f32_e32 v25, v25
	v_pk_mul_f32 v[26:27], v[20:21], v[20:21]
	v_add_f32_e32 v25, 1.0, v25
	v_rcp_f32_e32 v29, v25
	s_nop 0
	v_pk_mul_f32 v[18:19], v[18:19], v[28:29]
	s_nop 0
	v_cvt_pk_bf16_f32 v18, v18, v19
	v_fmamk_f32 v19, v26, 0xbdd2d3e8, v178
	v_mul_f32_e32 v19, v20, v19
	v_exp_f32_e32 v19, v19
	s_nop 0
	v_add_f32_e32 v19, 1.0, v19
	v_rcp_f32_e32 v26, v19
	v_fmamk_f32 v19, v27, 0xbdd2d3e8, v178
	v_mul_f32_e32 v19, v21, v19
	v_exp_f32_e32 v19, v19
	s_nop 0
	v_add_f32_e32 v19, 1.0, v19
	v_rcp_f32_e32 v27, v19
	s_nop 0
	v_pk_mul_f32 v[20:21], v[20:21], v[26:27]
	s_nop 0
	v_cvt_pk_bf16_f32 v19, v20, v21
	v_or_b32_e32 v20, v24, v157
	v_ashrrev_i32_e32 v21, 31, v20
	v_lshlrev_b64 v[20:21], 11, v[20:21]
	v_lshl_add_u64 v[20:21], v[144:145], 0, v[20:21]
	global_store_dwordx2 v[20:21], v[18:19], off
	s_nop 1
	v_mov_b32_e32 v18, v244
	v_mov_b32_e32 v19, v245
	v_lshlrev_b32_e32 v20, 16, v18
	v_and_b32_e32 v21, 0xffff0000, v18
	v_pk_fma_f32 v[10:11], v[14:15], v[20:21], v[10:11]
	s_nop 0
	v_pk_mul_f32 v[20:21], v[10:11], v[10:11]
	s_nop 0
	v_fmamk_f32 v18, v20, 0xbdd2d3e8, v178
	v_mul_f32_e32 v18, v10, v18
	v_exp_f32_e32 v18, v18
	s_nop 0
	v_add_f32_e32 v18, 1.0, v18
	v_rcp_f32_e32 v20, v18
	v_fmamk_f32 v18, v21, 0xbdd2d3e8, v178
	v_mul_f32_e32 v18, v11, v18
	v_exp_f32_e32 v18, v18
	s_nop 0
	v_add_f32_e32 v18, 1.0, v18
	v_rcp_f32_e32 v21, v18
	v_lshlrev_b32_e32 v18, 16, v19
	v_and_b32_e32 v19, 0xffff0000, v19
	v_pk_fma_f32 v[12:13], v[16:17], v[18:19], v[12:13]
	v_pk_mul_f32 v[10:11], v[10:11], v[20:21]
	v_pk_mul_f32 v[18:19], v[12:13], v[12:13]
	v_cvt_pk_bf16_f32 v10, v10, v11
	v_fmamk_f32 v11, v18, 0xbdd2d3e8, v178
	v_mul_f32_e32 v11, v12, v11
	v_exp_f32_e32 v11, v11
	s_nop 0
	v_add_f32_e32 v11, 1.0, v11
	v_rcp_f32_e32 v18, v11
	v_fmamk_f32 v11, v19, 0xbdd2d3e8, v178
	v_mul_f32_e32 v11, v13, v11
	v_exp_f32_e32 v11, v11
	s_nop 0
	v_add_f32_e32 v11, 1.0, v11
	v_rcp_f32_e32 v19, v11
	s_nop 0
	v_pk_mul_f32 v[12:13], v[12:13], v[18:19]
	s_nop 0
	v_cvt_pk_bf16_f32 v11, v12, v13
	v_or_b32_e32 v12, v24, v158
	v_ashrrev_i32_e32 v13, 31, v12
	v_lshlrev_b64 v[12:13], 11, v[12:13]
	v_lshl_add_u64 v[12:13], v[144:145], 0, v[12:13]
	global_store_dwordx2 v[12:13], v[10:11], off
	s_nop 1
	v_mov_b32_e32 v10, v246
	v_mov_b32_e32 v11, v247
	v_lshlrev_b32_e32 v12, 16, v10
	v_and_b32_e32 v13, 0xffff0000, v10
	v_pk_fma_f32 v[6:7], v[14:15], v[12:13], v[6:7]
	s_nop 0
	v_pk_mul_f32 v[12:13], v[6:7], v[6:7]
	s_nop 0
	v_fmamk_f32 v10, v12, 0xbdd2d3e8, v178
	v_mul_f32_e32 v10, v6, v10
	v_exp_f32_e32 v10, v10
	s_nop 0
	v_add_f32_e32 v10, 1.0, v10
	v_rcp_f32_e32 v12, v10
	v_fmamk_f32 v10, v13, 0xbdd2d3e8, v178
	v_mul_f32_e32 v10, v7, v10
	v_exp_f32_e32 v10, v10
	s_nop 0
	v_add_f32_e32 v10, 1.0, v10
	v_rcp_f32_e32 v13, v10
	v_lshlrev_b32_e32 v10, 16, v11
	v_and_b32_e32 v11, 0xffff0000, v11
	v_pk_fma_f32 v[8:9], v[16:17], v[10:11], v[8:9]
	v_pk_mul_f32 v[6:7], v[6:7], v[12:13]
	v_pk_mul_f32 v[10:11], v[8:9], v[8:9]
	v_cvt_pk_bf16_f32 v6, v6, v7
	v_fmamk_f32 v7, v10, 0xbdd2d3e8, v178
	v_mul_f32_e32 v7, v8, v7
	v_exp_f32_e32 v7, v7
	s_nop 0
	v_add_f32_e32 v7, 1.0, v7
	v_rcp_f32_e32 v10, v7
	v_fmamk_f32 v7, v11, 0xbdd2d3e8, v178
	v_mul_f32_e32 v7, v9, v7
	v_exp_f32_e32 v7, v7
	s_nop 0
	v_add_f32_e32 v7, 1.0, v7
	v_rcp_f32_e32 v11, v7
	s_nop 0
	v_pk_mul_f32 v[8:9], v[8:9], v[10:11]
	s_nop 0
	v_cvt_pk_bf16_f32 v7, v8, v9
	v_or_b32_e32 v8, v24, v159
	v_ashrrev_i32_e32 v9, 31, v8
	v_lshlrev_b64 v[8:9], 11, v[8:9]
	v_lshl_add_u64 v[8:9], v[144:145], 0, v[8:9]
	global_store_dwordx2 v[8:9], v[6:7], off
	s_nop 1
	v_mov_b32_e32 v6, v248
	v_mov_b32_e32 v7, v249
	v_lshlrev_b32_e32 v8, 16, v6
	v_and_b32_e32 v9, 0xffff0000, v6
	v_pk_fma_f32 v[2:3], v[14:15], v[8:9], v[2:3]
	s_nop 0
	v_pk_mul_f32 v[8:9], v[2:3], v[2:3]
	s_nop 0
	v_fmamk_f32 v6, v8, 0xbdd2d3e8, v178
	v_mul_f32_e32 v6, v2, v6
	v_exp_f32_e32 v6, v6
	s_nop 0
	v_add_f32_e32 v6, 1.0, v6
	v_rcp_f32_e32 v8, v6
	v_fmamk_f32 v6, v9, 0xbdd2d3e8, v178
	v_mul_f32_e32 v6, v3, v6
	v_exp_f32_e32 v6, v6
	s_nop 0
	v_add_f32_e32 v6, 1.0, v6
	v_rcp_f32_e32 v9, v6
	v_lshlrev_b32_e32 v6, 16, v7
	v_and_b32_e32 v7, 0xffff0000, v7
	v_pk_fma_f32 v[4:5], v[16:17], v[6:7], v[4:5]
	v_pk_mul_f32 v[2:3], v[2:3], v[8:9]
	v_pk_mul_f32 v[6:7], v[4:5], v[4:5]
	v_cvt_pk_bf16_f32 v2, v2, v3
	v_fmamk_f32 v3, v6, 0xbdd2d3e8, v178
	v_mul_f32_e32 v3, v4, v3
	v_exp_f32_e32 v3, v3
	s_nop 0
	v_add_f32_e32 v3, 1.0, v3
	v_rcp_f32_e32 v6, v3
	v_fmamk_f32 v3, v7, 0xbdd2d3e8, v178
	v_mul_f32_e32 v3, v5, v3
	v_exp_f32_e32 v3, v3
	s_nop 0
	v_add_f32_e32 v3, 1.0, v3
	v_rcp_f32_e32 v7, v3
	s_nop 0
	v_pk_mul_f32 v[4:5], v[4:5], v[6:7]
	s_nop 0
	v_cvt_pk_bf16_f32 v3, v4, v5
	v_or_b32_e32 v4, v24, v160
	v_ashrrev_i32_e32 v5, 31, v4
	v_lshlrev_b64 v[4:5], 11, v[4:5]
	v_lshl_add_u64 v[4:5], v[144:145], 0, v[4:5]
	global_store_dwordx2 v[4:5], v[2:3], off
	s_mov_b32 s2, s100
	s_waitcnt lgkmcnt(0)
	s_add_i32 s65, s2, s65
	s_cmpk_gt_i32 s65, 0x1ff
	s_cbranch_scc1 .LBB0_127
